# MLA loop: re-spaced PV/QK MFMAs against VALU (PV1 in max chain, PV4 last, 16 exps per gap), on top of trim + fp6 no-setprio
# speedup vs baseline: 1.0141x; 1.0024x over previous
.LBB0_710:
	s_mov_b32 s35, s4
	s_mov_b32 s4, s52
	global_load_dwordx4 v[204:207], v192, s[98:99] offset:128
	global_load_dwordx4 v[208:211], v188, s[98:99]
	global_load_dwordx2 v[218:219], v214, s[98:99] offset:-2048
	ds_read_b128 v[118:121], v199 offset:17424
	ds_read_b128 v[114:117], v199 offset:17408
	ds_read_b128 v[130:133], v199 offset:22016
	ds_read_b128 v[134:137], v199 offset:22032
	ds_read_b128 v[156:159], v199 offset:17488
	ds_read_b128 v[238:241], v199 offset:17472
	s_waitcnt lgkmcnt(4)
	v_add_f32_e32 v160, v86, v82
	v_mfma_scale_f32_32x32x64_f8f6f4 v[114:129], v[114:119], v[168:173], v[50:65], v120, v194 op_sel_hi:[0,0,0] cbsz:2 blgp:2
	v_cvt_pk_fp8_f32 v154, v82, v83
	v_cvt_pk_fp8_f32 v155, v98, v99
	v_cvt_pk_fp8_f32 v154, v84, v85 op_sel:[0,0,1]
	v_cvt_pk_fp8_f32 v155, v100, v101 op_sel:[0,0,1]
	v_add_f32_e32 v82, v87, v83
	v_add_f32_e32 v83, v88, v84
	v_permlane32_swap_b32_e32 v154, v155
	ds_read_b128 v[244:247], v199 offset:22080
	ds_read_b128 v[248:251], v199 offset:22096
	v_add_f32_e32 v84, v89, v85
	s_waitcnt lgkmcnt(3)
	v_mfma_scale_f32_32x32x64_f8f6f4 v[130:145], v[130:135], v[168:173], v[50:65], v136, v194 op_sel_hi:[0,0,0] cbsz:2 blgp:2
	v_add_f32_e32 v85, v90, v160
	v_add_f32_e32 v82, v91, v82
	v_mov_b32_e32 v242, v156
	v_mov_b32_e32 v243, v157
	v_add_f32_e32 v83, v92, v83
	v_add_f32_e32 v84, v93, v84
	v_add_f32_e32 v159, v94, v85
	v_add_f32_e32 v160, v95, v82
	v_add_f32_e32 v161, v96, v83
	v_add_f32_e32 v186, v97, v84
	ds_read_b128 v[230:233], v222 offset:5120
	ds_read_b128 v[234:237], v222 offset:5136
	s_waitcnt lgkmcnt(4)
	v_mfma_scale_f32_32x32x64_f8f6f4 v[114:129], v[238:243], v[162:167], v[114:129], v158, v190 op_sel_hi:[0,0,0] cbsz:2 blgp:2
	v_cvt_pk_fp8_f32 v156, v86, v87
	v_cvt_pk_fp8_f32 v157, v102, v103
	v_cvt_pk_fp8_f32 v156, v88, v89 op_sel:[0,0,1]
	v_cvt_pk_fp8_f32 v157, v104, v105 op_sel:[0,0,1]
	v_add_f32_e32 v98, v98, v159
	v_add_f32_e32 v99, v99, v160
	v_permlane32_swap_b32_e32 v156, v157
	v_add_f32_e32 v100, v100, v161
	v_add_f32_e32 v101, v101, v186
	v_add_f32_e32 v98, v102, v98
	ds_read_b128 v[82:85], v222 offset:7680
	ds_read_b128 v[86:89], v222 offset:7696
	s_waitcnt lgkmcnt(4)
	v_mfma_scale_f32_32x32x64_f8f6f4 v[130:145], v[244:249], v[162:167], v[130:145], v250, v190 op_sel_hi:[0,0,0] cbsz:2 blgp:2
	v_cvt_pk_fp8_f32 v158, v90, v91
	v_cvt_pk_fp8_f32 v159, v106, v107
	v_cvt_pk_fp8_f32 v158, v92, v93 op_sel:[0,0,1]
	v_cvt_pk_fp8_f32 v159, v108, v109 op_sel:[0,0,1]
	v_add_f32_e32 v90, v103, v99
	v_add_f32_e32 v91, v104, v100
	v_permlane32_swap_b32_e32 v158, v159
	v_add_f32_e32 v92, v105, v101
	s_waitcnt lgkmcnt(2)
	v_mfma_scale_f32_32x32x64_f8f6f4 v[114:129], v[230:237], v[146:153], v[114:129], v220, v1 op_sel_hi:[0,0,0]
	v_add_f32_e32 v93, v106, v98
	v_add_f32_e32 v90, v107, v90
	v_add_f32_e32 v91, v108, v91
	v_add_f32_e32 v92, v109, v92
	v_add_f32_e32 v93, v110, v93
	v_add_f32_e32 v90, v111, v90
	v_add_f32_e32 v91, v112, v91
	v_add_f32_e32 v92, v113, v92
	v_cvt_pk_fp8_f32 v160, v94, v95
	v_cvt_pk_fp8_f32 v161, v110, v111
	v_cvt_pk_fp8_f32 v160, v96, v97 op_sel:[0,0,1]
	v_cvt_pk_fp8_f32 v161, v112, v113 op_sel:[0,0,1]
	s_waitcnt lgkmcnt(0)
	v_mfma_scale_f32_32x32x64_f8f6f4 v[130:145], v[82:89], v[146:153], v[130:145], v220, v1 op_sel_hi:[0,0,0]
	v_add_f32_e32 v82, v93, v90
	v_add_f32_e32 v83, v91, v92
	v_permlane32_swap_b32_e32 v160, v161
	v_add_f32_e32 v229, v82, v83
	v_mov_b32_e32 v230, v229
	v_add_u32_e32 v82, s5, v224
	s_waitcnt vmcnt(0)
	ds_write_b128 v82, v[204:207]
	ds_write_b128 v225, v[208:211] offset:49152
	ds_write_b64 v226, v[218:219]
	v_add_u32_e32 v98, s4, v191
	ds_read_b128 v[90:93], v98
	ds_read_b128 v[94:97], v98 offset:16
	v_max3_f32 v82, v114, s88, v115
	v_max3_f32 v82, v82, v116, v117
	v_max3_f32 v82, v82, v118, v119
	v_permlane32_swap_b32_e32 v229, v230
	v_max3_f32 v99, v82, v120, v121
	ds_read_b128 v[82:85], v98 offset:2560
	ds_read_b128 v[86:89], v98 offset:2576
	v_max3_f32 v99, v99, v122, v123
	v_max3_f32 v99, v99, v124, v125
	v_max3_f32 v99, v99, v126, v127
	v_max3_f32 v99, v99, v128, v129
	s_waitcnt lgkmcnt(2)
	v_mfma_scale_f32_32x32x64_f8f6f4 v[66:81], v[90:97], v[154:161], v[66:81], v220, v220 op_sel_hi:[0,0,0]
	v_max3_f32 v99, v99, v130, v131
	v_max3_f32 v99, v99, v132, v133
	v_max3_f32 v99, v99, v134, v135
	v_max3_f32 v99, v99, v136, v137
	v_max3_f32 v99, v99, v138, v139
	v_max3_f32 v99, v99, v140, v141
	v_max3_f32 v99, v99, v142, v143
	v_max3_f32 v99, v99, v144, v145
	v_mov_b32_e32 v100, v99
	v_mov_b32_e32 v186, 1.0
	s_nop 0
	v_permlane32_swap_b32_e32 v99, v100
	v_max_f32_e32 v99, v99, v100
	v_cmp_ge_f32_e32 vcc, s89, v99
	s_cmp_eq_u64 vcc, exec
	s_cbranch_scc1 .LBB0_712
	v_add_f32_e32 v99, -4.0, v99
	v_max_f32_e32 v99, 0, v99
	v_exp_f32_e64 v186, -v99
	v_sub_f32_e32 v129, v129, v99
	v_sub_f32_e32 v128, v128, v99
	v_sub_f32_e32 v127, v127, v99
	v_sub_f32_e32 v126, v126, v99
	v_sub_f32_e32 v125, v125, v99
	v_sub_f32_e32 v124, v124, v99
	v_sub_f32_e32 v123, v123, v99
	v_sub_f32_e32 v122, v122, v99
	v_sub_f32_e32 v121, v121, v99
	v_sub_f32_e32 v120, v120, v99
	v_sub_f32_e32 v119, v119, v99
	v_sub_f32_e32 v118, v118, v99
	v_sub_f32_e32 v117, v117, v99
	v_sub_f32_e32 v116, v116, v99
	v_sub_f32_e32 v115, v115, v99
	v_sub_f32_e32 v114, v114, v99
	v_sub_f32_e32 v145, v145, v99
	v_sub_f32_e32 v144, v144, v99
	v_sub_f32_e32 v143, v143, v99
	v_sub_f32_e32 v142, v142, v99
	v_sub_f32_e32 v141, v141, v99
	v_sub_f32_e32 v140, v140, v99
	v_sub_f32_e32 v139, v139, v99
	v_sub_f32_e32 v138, v138, v99
	v_sub_f32_e32 v137, v137, v99
	v_sub_f32_e32 v136, v136, v99
	v_sub_f32_e32 v135, v135, v99
	v_sub_f32_e32 v134, v134, v99
	v_sub_f32_e32 v133, v133, v99
	v_sub_f32_e32 v132, v132, v99
	v_sub_f32_e32 v131, v131, v99
	v_sub_f32_e32 v130, v130, v99
	v_sub_f32_e32 v65, v65, v99
	v_sub_f32_e32 v64, v64, v99
	v_sub_f32_e32 v63, v63, v99
	v_sub_f32_e32 v62, v62, v99
	v_sub_f32_e32 v61, v61, v99
	v_sub_f32_e32 v60, v60, v99
	v_sub_f32_e32 v59, v59, v99
	v_sub_f32_e32 v58, v58, v99
	v_sub_f32_e32 v57, v57, v99
	v_sub_f32_e32 v56, v56, v99
	v_sub_f32_e32 v55, v55, v99
	v_sub_f32_e32 v54, v54, v99
	v_sub_f32_e32 v53, v53, v99
	v_sub_f32_e32 v52, v52, v99
	v_sub_f32_e32 v51, v51, v99
	v_sub_f32_e32 v50, v50, v99
.LBB0_712:
	s_waitcnt lgkmcnt(0)
	v_mfma_scale_f32_32x32x64_f8f6f4 v[34:49], v[82:89], v[154:161], v[34:49], v220, v220 op_sel_hi:[0,0,0]
	ds_read_b128 v[82:85], v98 offset:5120
	ds_read_b128 v[86:89], v98 offset:5136
	v_exp_f32_e32 v114, v114
	v_exp_f32_e32 v115, v115
	v_exp_f32_e32 v116, v116
	v_exp_f32_e32 v117, v117
	v_exp_f32_e32 v118, v118
	v_exp_f32_e32 v119, v119
	v_exp_f32_e32 v120, v120
	v_exp_f32_e32 v121, v121
	v_exp_f32_e32 v122, v122
	v_exp_f32_e32 v123, v123
	v_exp_f32_e32 v124, v124
	v_exp_f32_e32 v125, v125
	v_exp_f32_e32 v126, v126
	v_exp_f32_e32 v127, v127
	v_exp_f32_e32 v128, v128
	v_exp_f32_e32 v129, v129
	s_waitcnt lgkmcnt(0)
	v_mfma_scale_f32_32x32x64_f8f6f4 v[18:33], v[82:89], v[154:161], v[18:33], v220, v220 op_sel_hi:[0,0,0]
	ds_read_b128 v[82:85], v98 offset:7680
	ds_read_b128 v[86:89], v98 offset:7696
	v_exp_f32_e32 v130, v130
	v_exp_f32_e32 v131, v131
	v_exp_f32_e32 v132, v132
	v_exp_f32_e32 v133, v133
	v_exp_f32_e32 v134, v134
	v_exp_f32_e32 v135, v135
	v_exp_f32_e32 v136, v136
	v_exp_f32_e32 v137, v137
	v_exp_f32_e32 v138, v138
	v_exp_f32_e32 v139, v139
	v_exp_f32_e32 v140, v140
	v_exp_f32_e32 v141, v141
	v_exp_f32_e32 v142, v142
	v_exp_f32_e32 v143, v143
	v_exp_f32_e32 v144, v144
	v_exp_f32_e32 v145, v145
	s_waitcnt lgkmcnt(0)
	v_mfma_scale_f32_32x32x64_f8f6f4 v[2:17], v[82:89], v[154:161], v[2:17], v220, v220 op_sel_hi:[0,0,0]
	v_cmp_gt_f32_e32 vcc, 1.0, v186
	s_cbranch_vccz .LBB0_714
	v_pk_mul_f32 v[80:81], v[80:81], v[186:187] op_sel_hi:[1,0]
	v_pk_mul_f32 v[78:79], v[78:79], v[186:187] op_sel_hi:[1,0]
	v_pk_mul_f32 v[76:77], v[76:77], v[186:187] op_sel_hi:[1,0]
	v_pk_mul_f32 v[74:75], v[74:75], v[186:187] op_sel_hi:[1,0]
	v_pk_mul_f32 v[72:73], v[72:73], v[186:187] op_sel_hi:[1,0]
	v_pk_mul_f32 v[70:71], v[70:71], v[186:187] op_sel_hi:[1,0]
	v_pk_mul_f32 v[68:69], v[68:69], v[186:187] op_sel_hi:[1,0]
	v_pk_mul_f32 v[66:67], v[66:67], v[186:187] op_sel_hi:[1,0]
	v_pk_mul_f32 v[48:49], v[48:49], v[186:187] op_sel_hi:[1,0]
	v_pk_mul_f32 v[46:47], v[46:47], v[186:187] op_sel_hi:[1,0]
	v_pk_mul_f32 v[44:45], v[44:45], v[186:187] op_sel_hi:[1,0]
	v_pk_mul_f32 v[42:43], v[42:43], v[186:187] op_sel_hi:[1,0]
	v_pk_mul_f32 v[40:41], v[40:41], v[186:187] op_sel_hi:[1,0]
	v_pk_mul_f32 v[38:39], v[38:39], v[186:187] op_sel_hi:[1,0]
	v_pk_mul_f32 v[36:37], v[36:37], v[186:187] op_sel_hi:[1,0]
	v_pk_mul_f32 v[34:35], v[34:35], v[186:187] op_sel_hi:[1,0]
	v_pk_mul_f32 v[32:33], v[186:187], v[32:33] op_sel_hi:[0,1]
	v_pk_mul_f32 v[30:31], v[186:187], v[30:31] op_sel_hi:[0,1]
	v_pk_mul_f32 v[28:29], v[186:187], v[28:29] op_sel_hi:[0,1]
	v_pk_mul_f32 v[26:27], v[186:187], v[26:27] op_sel_hi:[0,1]
	v_pk_mul_f32 v[24:25], v[186:187], v[24:25] op_sel_hi:[0,1]
	v_pk_mul_f32 v[22:23], v[186:187], v[22:23] op_sel_hi:[0,1]
	v_pk_mul_f32 v[20:21], v[186:187], v[20:21] op_sel_hi:[0,1]
	v_pk_mul_f32 v[18:19], v[186:187], v[18:19] op_sel_hi:[0,1]
	v_pk_mul_f32 v[16:17], v[186:187], v[16:17] op_sel_hi:[0,1]
	v_pk_mul_f32 v[14:15], v[186:187], v[14:15] op_sel_hi:[0,1]
	v_pk_mul_f32 v[12:13], v[186:187], v[12:13] op_sel_hi:[0,1]
	v_pk_mul_f32 v[10:11], v[186:187], v[10:11] op_sel_hi:[0,1]
	v_pk_mul_f32 v[8:9], v[186:187], v[8:9] op_sel_hi:[0,1]
	v_pk_mul_f32 v[6:7], v[186:187], v[6:7] op_sel_hi:[0,1]
	v_pk_mul_f32 v[4:5], v[186:187], v[4:5] op_sel_hi:[0,1]
	v_pk_mul_f32 v[2:3], v[186:187], v[2:3] op_sel_hi:[0,1]
.LBB0_714:
	s_barrier
	global_load_dwordx4 v[204:207], v192, s[98:99] offset:192
	global_load_dwordx4 v[208:211], v189, s[98:99]
	global_load_dwordx2 v[196:197], v214, s[98:99] offset:2048
	ds_read_b128 v[86:89], v223 offset:49168
	ds_read_b128 v[82:85], v223 offset:49152
	ds_read_b128 v[98:101], v223 offset:53760
	ds_read_b128 v[102:105], v223 offset:53776
	ds_read_b128 v[156:159], v223 offset:49232
	ds_read_b128 v[240:243], v223 offset:49216
	s_waitcnt lgkmcnt(4)
	v_add_f32_e32 v160, v118, v114
	v_mfma_scale_f32_32x32x64_f8f6f4 v[82:97], v[82:87], v[174:179], v[50:65], v88, v198 op_sel_hi:[0,0,0] cbsz:2 blgp:2
	v_cvt_pk_fp8_f32 v154, v114, v115
	v_cvt_pk_fp8_f32 v155, v130, v131
	v_cvt_pk_fp8_f32 v154, v116, v117 op_sel:[0,0,1]
	v_cvt_pk_fp8_f32 v155, v132, v133 op_sel:[0,0,1]
	v_add_f32_e32 v114, v119, v115
	v_add_f32_e32 v115, v120, v116
	v_permlane32_swap_b32_e32 v154, v155
	ds_read_b128 v[246:249], v223 offset:53824
	ds_read_b128 v[216:219], v223 offset:53840
	v_add_f32_e32 v116, v121, v117
	s_waitcnt lgkmcnt(3)
	v_mfma_scale_f32_32x32x64_f8f6f4 v[98:113], v[98:103], v[174:179], v[50:65], v104, v198 op_sel_hi:[0,0,0] cbsz:2 blgp:2
	v_add_f32_e32 v117, v122, v160
	v_add_f32_e32 v114, v123, v114
	v_mov_b32_e32 v244, v156
	v_mov_b32_e32 v245, v157
	v_add_f32_e32 v115, v124, v115
	v_add_f32_e32 v116, v125, v116
	v_add_f32_e32 v159, v126, v117
	v_add_f32_e32 v160, v127, v114
	v_add_f32_e32 v161, v128, v115
	v_add_f32_e32 v200, v129, v116
	ds_read_b128 v[232:235], v222
	ds_read_b128 v[236:239], v222 offset:16
	s_waitcnt lgkmcnt(4)
	v_mfma_scale_f32_32x32x64_f8f6f4 v[82:97], v[240:245], v[180:185], v[82:97], v158, v202 op_sel_hi:[0,0,0] cbsz:2 blgp:2
	v_cvt_pk_fp8_f32 v156, v118, v119
	v_cvt_pk_fp8_f32 v157, v134, v135
	v_cvt_pk_fp8_f32 v156, v120, v121 op_sel:[0,0,1]
	v_cvt_pk_fp8_f32 v157, v136, v137 op_sel:[0,0,1]
	v_add_f32_e32 v130, v130, v159
	v_add_f32_e32 v131, v131, v160
	v_permlane32_swap_b32_e32 v156, v157
	s_waitcnt lgkmcnt(2)
	v_mov_b32_e32 v250, v216
	v_mov_b32_e32 v251, v217
	v_add_f32_e32 v132, v132, v161
	v_add_f32_e32 v133, v133, v200
	v_add_f32_e32 v130, v134, v130
	ds_read_b128 v[114:117], v222 offset:2560
	ds_read_b128 v[118:121], v222 offset:2576
	v_mfma_scale_f32_32x32x64_f8f6f4 v[98:113], v[246:251], v[180:185], v[98:113], v218, v202 op_sel_hi:[0,0,0] cbsz:2 blgp:2
	v_cvt_pk_fp8_f32 v158, v122, v123
	v_cvt_pk_fp8_f32 v159, v138, v139
	v_cvt_pk_fp8_f32 v158, v124, v125 op_sel:[0,0,1]
	v_cvt_pk_fp8_f32 v159, v140, v141 op_sel:[0,0,1]
	v_add_f32_e32 v122, v135, v131
	v_add_f32_e32 v123, v136, v132
	v_permlane32_swap_b32_e32 v158, v159
	v_add_f32_e32 v124, v137, v133
	s_waitcnt lgkmcnt(2)
	v_mfma_scale_f32_32x32x64_f8f6f4 v[82:97], v[232:239], v[146:153], v[82:97], v220, v1 op_sel_hi:[0,0,0]
	v_add_f32_e32 v125, v138, v130
	v_add_f32_e32 v122, v139, v122
	v_add_f32_e32 v123, v140, v123
	v_add_f32_e32 v124, v141, v124
	v_add_f32_e32 v125, v142, v125
	v_add_f32_e32 v122, v143, v122
	v_add_f32_e32 v123, v144, v123
	v_add_f32_e32 v124, v145, v124
	v_cvt_pk_fp8_f32 v160, v126, v127
	v_cvt_pk_fp8_f32 v161, v142, v143
	v_cvt_pk_fp8_f32 v160, v128, v129 op_sel:[0,0,1]
	v_cvt_pk_fp8_f32 v161, v144, v145 op_sel:[0,0,1]
	s_waitcnt lgkmcnt(0)
	v_mfma_scale_f32_32x32x64_f8f6f4 v[98:113], v[114:121], v[146:153], v[98:113], v220, v1 op_sel_hi:[0,0,0]
	v_add_f32_e32 v114, v125, v122
	v_add_f32_e32 v115, v123, v124
	v_permlane32_swap_b32_e32 v160, v161
	v_add_f32_e32 v130, v114, v115
	v_mov_b32_e32 v131, v130
	v_add_u32_e32 v114, s4, v224
	s_waitcnt vmcnt(0)
	ds_write_b128 v114, v[204:207]
	ds_write_b128 v203, v[208:211]
	ds_write_b64 v227, v[196:197]
	v_add_u32_e32 v132, s35, v191
	ds_read_b128 v[122:125], v132
	ds_read_b128 v[126:129], v132 offset:16
	v_max3_f32 v114, v82, s88, v83
	v_max3_f32 v114, v114, v84, v85
	v_max3_f32 v114, v114, v86, v87
	v_permlane32_swap_b32_e32 v130, v131
	v_max3_f32 v133, v114, v88, v89
	ds_read_b128 v[114:117], v132 offset:2560
	ds_read_b128 v[118:121], v132 offset:2576
	v_max3_f32 v133, v133, v90, v91
	v_max3_f32 v133, v133, v92, v93
	v_max3_f32 v133, v133, v94, v95
	v_max3_f32 v133, v133, v96, v97
	s_waitcnt lgkmcnt(2)
	v_mfma_scale_f32_32x32x64_f8f6f4 v[66:81], v[122:129], v[154:161], v[66:81], v220, v220 op_sel_hi:[0,0,0]
	v_max3_f32 v133, v133, v98, v99
	v_max3_f32 v133, v133, v100, v101
	v_max3_f32 v133, v133, v102, v103
	v_max3_f32 v133, v133, v104, v105
	v_max3_f32 v133, v133, v106, v107
	v_max3_f32 v133, v133, v108, v109
	v_max3_f32 v133, v133, v110, v111
	v_max3_f32 v133, v133, v112, v113
	v_mov_b32_e32 v134, v133
	v_mov_b32_e32 v138, 1.0
	s_nop 0
	v_permlane32_swap_b32_e32 v133, v134
	v_max_f32_e32 v133, v133, v134
	v_cmp_ge_f32_e32 vcc, s89, v133
	s_cmp_eq_u64 vcc, exec
	s_cbranch_scc1 .LBB0_716
	v_add_f32_e32 v133, -4.0, v133
	v_max_f32_e32 v133, 0, v133
	v_exp_f32_e64 v138, -v133
	v_sub_f32_e32 v97, v97, v133
	v_sub_f32_e32 v96, v96, v133
	v_sub_f32_e32 v95, v95, v133
	v_sub_f32_e32 v94, v94, v133
	v_sub_f32_e32 v93, v93, v133
	v_sub_f32_e32 v92, v92, v133
	v_sub_f32_e32 v91, v91, v133
	v_sub_f32_e32 v90, v90, v133
	v_sub_f32_e32 v89, v89, v133
	v_sub_f32_e32 v88, v88, v133
	v_sub_f32_e32 v87, v87, v133
	v_sub_f32_e32 v86, v86, v133
	v_sub_f32_e32 v85, v85, v133
	v_sub_f32_e32 v84, v84, v133
	v_sub_f32_e32 v83, v83, v133
	v_sub_f32_e32 v82, v82, v133
	v_sub_f32_e32 v113, v113, v133
	v_sub_f32_e32 v112, v112, v133
	v_sub_f32_e32 v111, v111, v133
	v_sub_f32_e32 v110, v110, v133
	v_sub_f32_e32 v109, v109, v133
	v_sub_f32_e32 v108, v108, v133
	v_sub_f32_e32 v107, v107, v133
	v_sub_f32_e32 v106, v106, v133
	v_sub_f32_e32 v105, v105, v133
	v_sub_f32_e32 v104, v104, v133
	v_sub_f32_e32 v103, v103, v133
	v_sub_f32_e32 v102, v102, v133
	v_sub_f32_e32 v101, v101, v133
	v_sub_f32_e32 v100, v100, v133
	v_sub_f32_e32 v99, v99, v133
	v_sub_f32_e32 v98, v98, v133
	v_sub_f32_e32 v65, v65, v133
	v_sub_f32_e32 v64, v64, v133
	v_sub_f32_e32 v63, v63, v133
	v_sub_f32_e32 v62, v62, v133
	v_sub_f32_e32 v61, v61, v133
	v_sub_f32_e32 v60, v60, v133
	v_sub_f32_e32 v59, v59, v133
	v_sub_f32_e32 v58, v58, v133
	v_sub_f32_e32 v57, v57, v133
	v_sub_f32_e32 v56, v56, v133
	v_sub_f32_e32 v55, v55, v133
	v_sub_f32_e32 v54, v54, v133
	v_sub_f32_e32 v53, v53, v133
	v_sub_f32_e32 v52, v52, v133
	v_sub_f32_e32 v51, v51, v133
	v_sub_f32_e32 v50, v50, v133
.LBB0_716:
	s_waitcnt lgkmcnt(0)
	v_mfma_scale_f32_32x32x64_f8f6f4 v[34:49], v[114:121], v[154:161], v[34:49], v220, v220 op_sel_hi:[0,0,0]
	ds_read_b128 v[114:117], v132 offset:5120
	ds_read_b128 v[118:121], v132 offset:5136
	v_exp_f32_e32 v82, v82
	v_exp_f32_e32 v83, v83
	v_exp_f32_e32 v84, v84
	v_exp_f32_e32 v85, v85
	v_exp_f32_e32 v86, v86
	v_exp_f32_e32 v87, v87
	v_exp_f32_e32 v88, v88
	v_exp_f32_e32 v89, v89
	v_exp_f32_e32 v90, v90
	v_exp_f32_e32 v91, v91
	v_exp_f32_e32 v92, v92
	v_exp_f32_e32 v93, v93
	v_exp_f32_e32 v94, v94
	v_exp_f32_e32 v95, v95
	v_exp_f32_e32 v96, v96
	v_exp_f32_e32 v97, v97
	s_waitcnt lgkmcnt(0)
	v_mfma_scale_f32_32x32x64_f8f6f4 v[18:33], v[114:121], v[154:161], v[18:33], v220, v220 op_sel_hi:[0,0,0]
	ds_read_b128 v[114:117], v132 offset:7680
	ds_read_b128 v[118:121], v132 offset:7696
	v_exp_f32_e32 v98, v98
	v_exp_f32_e32 v99, v99
	v_exp_f32_e32 v100, v100
	v_exp_f32_e32 v101, v101
	v_exp_f32_e32 v102, v102
	v_exp_f32_e32 v103, v103
	v_exp_f32_e32 v104, v104
	v_exp_f32_e32 v105, v105
	v_exp_f32_e32 v106, v106
	v_exp_f32_e32 v107, v107
	v_exp_f32_e32 v108, v108
	v_exp_f32_e32 v109, v109
	v_exp_f32_e32 v110, v110
	v_exp_f32_e32 v111, v111
	v_exp_f32_e32 v112, v112
	v_exp_f32_e32 v113, v113
	s_waitcnt lgkmcnt(0)
	v_mfma_scale_f32_32x32x64_f8f6f4 v[2:17], v[114:121], v[154:161], v[2:17], v220, v220 op_sel_hi:[0,0,0]
	v_cmp_gt_f32_e32 vcc, 1.0, v138
	s_cbranch_vccz .LBB0_718
	v_pk_mul_f32 v[80:81], v[80:81], v[138:139] op_sel_hi:[1,0]
	v_pk_mul_f32 v[78:79], v[78:79], v[138:139] op_sel_hi:[1,0]
	v_pk_mul_f32 v[76:77], v[76:77], v[138:139] op_sel_hi:[1,0]
	v_pk_mul_f32 v[74:75], v[74:75], v[138:139] op_sel_hi:[1,0]
	v_pk_mul_f32 v[72:73], v[72:73], v[138:139] op_sel_hi:[1,0]
	v_pk_mul_f32 v[70:71], v[70:71], v[138:139] op_sel_hi:[1,0]
	v_pk_mul_f32 v[68:69], v[68:69], v[138:139] op_sel_hi:[1,0]
	v_pk_mul_f32 v[66:67], v[66:67], v[138:139] op_sel_hi:[1,0]
	v_pk_mul_f32 v[48:49], v[48:49], v[138:139] op_sel_hi:[1,0]
	v_pk_mul_f32 v[46:47], v[46:47], v[138:139] op_sel_hi:[1,0]
	v_pk_mul_f32 v[44:45], v[44:45], v[138:139] op_sel_hi:[1,0]
	v_pk_mul_f32 v[42:43], v[42:43], v[138:139] op_sel_hi:[1,0]
	v_pk_mul_f32 v[40:41], v[40:41], v[138:139] op_sel_hi:[1,0]
	v_pk_mul_f32 v[38:39], v[38:39], v[138:139] op_sel_hi:[1,0]
	v_pk_mul_f32 v[36:37], v[36:37], v[138:139] op_sel_hi:[1,0]
	v_pk_mul_f32 v[34:35], v[34:35], v[138:139] op_sel_hi:[1,0]
	v_pk_mul_f32 v[32:33], v[138:139], v[32:33] op_sel_hi:[0,1]
	v_pk_mul_f32 v[30:31], v[138:139], v[30:31] op_sel_hi:[0,1]
	v_pk_mul_f32 v[28:29], v[138:139], v[28:29] op_sel_hi:[0,1]
	v_pk_mul_f32 v[26:27], v[138:139], v[26:27] op_sel_hi:[0,1]
	v_pk_mul_f32 v[24:25], v[138:139], v[24:25] op_sel_hi:[0,1]
	v_pk_mul_f32 v[22:23], v[138:139], v[22:23] op_sel_hi:[0,1]
	v_pk_mul_f32 v[20:21], v[138:139], v[20:21] op_sel_hi:[0,1]
	v_pk_mul_f32 v[18:19], v[138:139], v[18:19] op_sel_hi:[0,1]
	v_pk_mul_f32 v[16:17], v[138:139], v[16:17] op_sel_hi:[0,1]
	v_pk_mul_f32 v[14:15], v[138:139], v[14:15] op_sel_hi:[0,1]
	v_pk_mul_f32 v[12:13], v[138:139], v[12:13] op_sel_hi:[0,1]
	v_pk_mul_f32 v[10:11], v[138:139], v[10:11] op_sel_hi:[0,1]
	v_pk_mul_f32 v[8:9], v[138:139], v[8:9] op_sel_hi:[0,1]
	v_pk_mul_f32 v[6:7], v[138:139], v[6:7] op_sel_hi:[0,1]
	v_pk_mul_f32 v[4:5], v[138:139], v[4:5] op_sel_hi:[0,1]
	v_pk_mul_f32 v[2:3], v[138:139], v[2:3] op_sel_hi:[0,1]

.LBB0_1733:
	s_mov_b32 s10, s4
	s_mov_b32 s4, s8
	global_load_dwordx4 v[204:207], v192, s[98:99] offset:128
	global_load_dwordx4 v[208:211], v188, s[98:99]
	global_load_dwordx2 v[218:219], v214, s[98:99] offset:-2048
	ds_read_b128 v[118:121], v199 offset:17424
	ds_read_b128 v[114:117], v199 offset:17408
	ds_read_b128 v[130:133], v199 offset:22016
	ds_read_b128 v[134:137], v199 offset:22032
	ds_read_b128 v[156:159], v199 offset:17488
	ds_read_b128 v[238:241], v199 offset:17472
	s_waitcnt lgkmcnt(4)
	v_add_f32_e32 v160, v86, v82
	v_mfma_scale_f32_32x32x64_f8f6f4 v[114:129], v[114:119], v[168:173], v[50:65], v120, v194 op_sel_hi:[0,0,0] cbsz:2 blgp:2
	v_cvt_pk_fp8_f32 v154, v82, v83
	v_cvt_pk_fp8_f32 v155, v98, v99
	v_cvt_pk_fp8_f32 v154, v84, v85 op_sel:[0,0,1]
	v_cvt_pk_fp8_f32 v155, v100, v101 op_sel:[0,0,1]
	v_add_f32_e32 v82, v87, v83
	v_add_f32_e32 v83, v88, v84
	v_permlane32_swap_b32_e32 v154, v155
	ds_read_b128 v[244:247], v199 offset:22080
	ds_read_b128 v[248:251], v199 offset:22096
	v_add_f32_e32 v84, v89, v85
	s_waitcnt lgkmcnt(3)
	v_mfma_scale_f32_32x32x64_f8f6f4 v[130:145], v[130:135], v[168:173], v[50:65], v136, v194 op_sel_hi:[0,0,0] cbsz:2 blgp:2
	v_add_f32_e32 v85, v90, v160
	v_add_f32_e32 v82, v91, v82
	v_mov_b32_e32 v242, v156
	v_mov_b32_e32 v243, v157
	v_add_f32_e32 v83, v92, v83
	v_add_f32_e32 v84, v93, v84
	v_add_f32_e32 v159, v94, v85
	v_add_f32_e32 v160, v95, v82
	v_add_f32_e32 v161, v96, v83
	v_add_f32_e32 v186, v97, v84
	ds_read_b128 v[230:233], v222 offset:5120
	ds_read_b128 v[234:237], v222 offset:5136
	s_waitcnt lgkmcnt(4)
	v_mfma_scale_f32_32x32x64_f8f6f4 v[114:129], v[238:243], v[162:167], v[114:129], v158, v190 op_sel_hi:[0,0,0] cbsz:2 blgp:2
	v_cvt_pk_fp8_f32 v156, v86, v87
	v_cvt_pk_fp8_f32 v157, v102, v103
	v_cvt_pk_fp8_f32 v156, v88, v89 op_sel:[0,0,1]
	v_cvt_pk_fp8_f32 v157, v104, v105 op_sel:[0,0,1]
	v_add_f32_e32 v98, v98, v159
	v_add_f32_e32 v99, v99, v160
	v_permlane32_swap_b32_e32 v156, v157
	v_add_f32_e32 v100, v100, v161
	v_add_f32_e32 v101, v101, v186
	v_add_f32_e32 v98, v102, v98
	ds_read_b128 v[82:85], v222 offset:7680
	ds_read_b128 v[86:89], v222 offset:7696
	s_waitcnt lgkmcnt(4)
	v_mfma_scale_f32_32x32x64_f8f6f4 v[130:145], v[244:249], v[162:167], v[130:145], v250, v190 op_sel_hi:[0,0,0] cbsz:2 blgp:2
	v_cvt_pk_fp8_f32 v158, v90, v91
	v_cvt_pk_fp8_f32 v159, v106, v107
	v_cvt_pk_fp8_f32 v158, v92, v93 op_sel:[0,0,1]
	v_cvt_pk_fp8_f32 v159, v108, v109 op_sel:[0,0,1]
	v_add_f32_e32 v90, v103, v99
	v_add_f32_e32 v91, v104, v100
	v_permlane32_swap_b32_e32 v158, v159
	v_add_f32_e32 v92, v105, v101
	s_waitcnt lgkmcnt(2)
	v_mfma_scale_f32_32x32x64_f8f6f4 v[114:129], v[230:237], v[146:153], v[114:129], v220, v1 op_sel_hi:[0,0,0]
	v_add_f32_e32 v93, v106, v98
	v_add_f32_e32 v90, v107, v90
	v_add_f32_e32 v91, v108, v91
	v_add_f32_e32 v92, v109, v92
	v_add_f32_e32 v93, v110, v93
	v_add_f32_e32 v90, v111, v90
	v_add_f32_e32 v91, v112, v91
	v_add_f32_e32 v92, v113, v92
	v_cvt_pk_fp8_f32 v160, v94, v95
	v_cvt_pk_fp8_f32 v161, v110, v111
	v_cvt_pk_fp8_f32 v160, v96, v97 op_sel:[0,0,1]
	v_cvt_pk_fp8_f32 v161, v112, v113 op_sel:[0,0,1]
	s_waitcnt lgkmcnt(0)
	v_mfma_scale_f32_32x32x64_f8f6f4 v[130:145], v[82:89], v[146:153], v[130:145], v220, v1 op_sel_hi:[0,0,0]
	v_add_f32_e32 v82, v93, v90
	v_add_f32_e32 v83, v91, v92
	v_permlane32_swap_b32_e32 v160, v161
	v_add_f32_e32 v229, v82, v83
	v_mov_b32_e32 v230, v229
	v_add_u32_e32 v82, s5, v224
	s_waitcnt vmcnt(0)
	ds_write_b128 v82, v[204:207]
	ds_write_b128 v225, v[208:211] offset:49152
	ds_write_b64 v226, v[218:219]
	v_add_u32_e32 v98, s4, v191
	ds_read_b128 v[90:93], v98
	ds_read_b128 v[94:97], v98 offset:16
	v_max3_f32 v82, v114, s87, v115
	v_max3_f32 v82, v82, v116, v117
	v_max3_f32 v82, v82, v118, v119
	v_permlane32_swap_b32_e32 v229, v230
	v_max3_f32 v99, v82, v120, v121
	ds_read_b128 v[82:85], v98 offset:2560
	ds_read_b128 v[86:89], v98 offset:2576
	v_max3_f32 v99, v99, v122, v123
	v_max3_f32 v99, v99, v124, v125
	v_max3_f32 v99, v99, v126, v127
	v_max3_f32 v99, v99, v128, v129
	s_waitcnt lgkmcnt(2)
	v_mfma_scale_f32_32x32x64_f8f6f4 v[66:81], v[90:97], v[154:161], v[66:81], v220, v220 op_sel_hi:[0,0,0]
	v_max3_f32 v99, v99, v130, v131
	v_max3_f32 v99, v99, v132, v133
	v_max3_f32 v99, v99, v134, v135
	v_max3_f32 v99, v99, v136, v137
	v_max3_f32 v99, v99, v138, v139
	v_max3_f32 v99, v99, v140, v141
	v_max3_f32 v99, v99, v142, v143
	v_max3_f32 v99, v99, v144, v145
	v_mov_b32_e32 v100, v99
	v_mov_b32_e32 v186, 1.0
	s_nop 0
	v_permlane32_swap_b32_e32 v99, v100
	v_max_f32_e32 v99, v99, v100
	v_cmp_ge_f32_e32 vcc, s88, v99
	s_cmp_eq_u64 vcc, exec
	s_cbranch_scc1 .LBB0_1735
	v_add_f32_e32 v99, -4.0, v99
	v_max_f32_e32 v99, 0, v99
	v_exp_f32_e64 v186, -v99
	v_sub_f32_e32 v129, v129, v99
	v_sub_f32_e32 v128, v128, v99
	v_sub_f32_e32 v127, v127, v99
	v_sub_f32_e32 v126, v126, v99
	v_sub_f32_e32 v125, v125, v99
	v_sub_f32_e32 v124, v124, v99
	v_sub_f32_e32 v123, v123, v99
	v_sub_f32_e32 v122, v122, v99
	v_sub_f32_e32 v121, v121, v99
	v_sub_f32_e32 v120, v120, v99
	v_sub_f32_e32 v119, v119, v99
	v_sub_f32_e32 v118, v118, v99
	v_sub_f32_e32 v117, v117, v99
	v_sub_f32_e32 v116, v116, v99
	v_sub_f32_e32 v115, v115, v99
	v_sub_f32_e32 v114, v114, v99
	v_sub_f32_e32 v145, v145, v99
	v_sub_f32_e32 v144, v144, v99
	v_sub_f32_e32 v143, v143, v99
	v_sub_f32_e32 v142, v142, v99
	v_sub_f32_e32 v141, v141, v99
	v_sub_f32_e32 v140, v140, v99
	v_sub_f32_e32 v139, v139, v99
	v_sub_f32_e32 v138, v138, v99
	v_sub_f32_e32 v137, v137, v99
	v_sub_f32_e32 v136, v136, v99
	v_sub_f32_e32 v135, v135, v99
	v_sub_f32_e32 v134, v134, v99
	v_sub_f32_e32 v133, v133, v99
	v_sub_f32_e32 v132, v132, v99
	v_sub_f32_e32 v131, v131, v99
	v_sub_f32_e32 v130, v130, v99
	v_sub_f32_e32 v65, v65, v99
	v_sub_f32_e32 v64, v64, v99
	v_sub_f32_e32 v63, v63, v99
	v_sub_f32_e32 v62, v62, v99
	v_sub_f32_e32 v61, v61, v99
	v_sub_f32_e32 v60, v60, v99
	v_sub_f32_e32 v59, v59, v99
	v_sub_f32_e32 v58, v58, v99
	v_sub_f32_e32 v57, v57, v99
	v_sub_f32_e32 v56, v56, v99
	v_sub_f32_e32 v55, v55, v99
	v_sub_f32_e32 v54, v54, v99
	v_sub_f32_e32 v53, v53, v99
	v_sub_f32_e32 v52, v52, v99
	v_sub_f32_e32 v51, v51, v99
	v_sub_f32_e32 v50, v50, v99

.LBB0_1737:
	s_barrier
	global_load_dwordx4 v[204:207], v192, s[98:99] offset:192
	global_load_dwordx4 v[208:211], v189, s[98:99]
	global_load_dwordx2 v[196:197], v214, s[98:99] offset:2048
	ds_read_b128 v[86:89], v223 offset:49168
	ds_read_b128 v[82:85], v223 offset:49152
	ds_read_b128 v[98:101], v223 offset:53760
	ds_read_b128 v[102:105], v223 offset:53776
	ds_read_b128 v[156:159], v223 offset:49232
	ds_read_b128 v[240:243], v223 offset:49216
	s_waitcnt lgkmcnt(4)
	v_add_f32_e32 v160, v118, v114
	v_mfma_scale_f32_32x32x64_f8f6f4 v[82:97], v[82:87], v[174:179], v[50:65], v88, v198 op_sel_hi:[0,0,0] cbsz:2 blgp:2
	v_cvt_pk_fp8_f32 v154, v114, v115
	v_cvt_pk_fp8_f32 v155, v130, v131
	v_cvt_pk_fp8_f32 v154, v116, v117 op_sel:[0,0,1]
	v_cvt_pk_fp8_f32 v155, v132, v133 op_sel:[0,0,1]
	v_add_f32_e32 v114, v119, v115
	v_add_f32_e32 v115, v120, v116
	v_permlane32_swap_b32_e32 v154, v155
	ds_read_b128 v[246:249], v223 offset:53824
	ds_read_b128 v[216:219], v223 offset:53840
	v_add_f32_e32 v116, v121, v117
	s_waitcnt lgkmcnt(3)
	v_mfma_scale_f32_32x32x64_f8f6f4 v[98:113], v[98:103], v[174:179], v[50:65], v104, v198 op_sel_hi:[0,0,0] cbsz:2 blgp:2
	v_add_f32_e32 v117, v122, v160
	v_add_f32_e32 v114, v123, v114
	v_mov_b32_e32 v244, v156
	v_mov_b32_e32 v245, v157
	v_add_f32_e32 v115, v124, v115
	v_add_f32_e32 v116, v125, v116
	v_add_f32_e32 v159, v126, v117
	v_add_f32_e32 v160, v127, v114
	v_add_f32_e32 v161, v128, v115
	v_add_f32_e32 v200, v129, v116
	ds_read_b128 v[232:235], v222
	ds_read_b128 v[236:239], v222 offset:16
	s_waitcnt lgkmcnt(4)
	v_mfma_scale_f32_32x32x64_f8f6f4 v[82:97], v[240:245], v[180:185], v[82:97], v158, v202 op_sel_hi:[0,0,0] cbsz:2 blgp:2
	v_cvt_pk_fp8_f32 v156, v118, v119
	v_cvt_pk_fp8_f32 v157, v134, v135
	v_cvt_pk_fp8_f32 v156, v120, v121 op_sel:[0,0,1]
	v_cvt_pk_fp8_f32 v157, v136, v137 op_sel:[0,0,1]
	v_add_f32_e32 v130, v130, v159
	v_add_f32_e32 v131, v131, v160
	v_permlane32_swap_b32_e32 v156, v157
	s_waitcnt lgkmcnt(2)
	v_mov_b32_e32 v250, v216
	v_mov_b32_e32 v251, v217
	v_add_f32_e32 v132, v132, v161
	v_add_f32_e32 v133, v133, v200
	v_add_f32_e32 v130, v134, v130
	ds_read_b128 v[114:117], v222 offset:2560
	ds_read_b128 v[118:121], v222 offset:2576
	v_mfma_scale_f32_32x32x64_f8f6f4 v[98:113], v[246:251], v[180:185], v[98:113], v218, v202 op_sel_hi:[0,0,0] cbsz:2 blgp:2
	v_cvt_pk_fp8_f32 v158, v122, v123
	v_cvt_pk_fp8_f32 v159, v138, v139
	v_cvt_pk_fp8_f32 v158, v124, v125 op_sel:[0,0,1]
	v_cvt_pk_fp8_f32 v159, v140, v141 op_sel:[0,0,1]
	v_add_f32_e32 v122, v135, v131
	v_add_f32_e32 v123, v136, v132
	v_permlane32_swap_b32_e32 v158, v159
	v_add_f32_e32 v124, v137, v133
	s_waitcnt lgkmcnt(2)
	v_mfma_scale_f32_32x32x64_f8f6f4 v[82:97], v[232:239], v[146:153], v[82:97], v220, v1 op_sel_hi:[0,0,0]
	v_add_f32_e32 v125, v138, v130
	v_add_f32_e32 v122, v139, v122
	v_add_f32_e32 v123, v140, v123
	v_add_f32_e32 v124, v141, v124
	v_add_f32_e32 v125, v142, v125
	v_add_f32_e32 v122, v143, v122
	v_add_f32_e32 v123, v144, v123
	v_add_f32_e32 v124, v145, v124
	v_cvt_pk_fp8_f32 v160, v126, v127
	v_cvt_pk_fp8_f32 v161, v142, v143
	v_cvt_pk_fp8_f32 v160, v128, v129 op_sel:[0,0,1]
	v_cvt_pk_fp8_f32 v161, v144, v145 op_sel:[0,0,1]
	s_waitcnt lgkmcnt(0)
	v_mfma_scale_f32_32x32x64_f8f6f4 v[98:113], v[114:121], v[146:153], v[98:113], v220, v1 op_sel_hi:[0,0,0]
	v_add_f32_e32 v114, v125, v122
	v_add_f32_e32 v115, v123, v124
	v_permlane32_swap_b32_e32 v160, v161
	v_add_f32_e32 v130, v114, v115
	v_mov_b32_e32 v131, v130
	v_add_u32_e32 v114, s4, v224
	s_waitcnt vmcnt(0)
	ds_write_b128 v114, v[204:207]
	ds_write_b128 v203, v[208:211]
	ds_write_b64 v227, v[196:197]
	v_add_u32_e32 v132, s10, v191
	ds_read_b128 v[122:125], v132
	ds_read_b128 v[126:129], v132 offset:16
	v_max3_f32 v114, v82, s87, v83
	v_max3_f32 v114, v114, v84, v85
	v_max3_f32 v114, v114, v86, v87
	v_permlane32_swap_b32_e32 v130, v131
	v_max3_f32 v133, v114, v88, v89
	ds_read_b128 v[114:117], v132 offset:2560
	ds_read_b128 v[118:121], v132 offset:2576
	v_max3_f32 v133, v133, v90, v91
	v_max3_f32 v133, v133, v92, v93
	v_max3_f32 v133, v133, v94, v95
	v_max3_f32 v133, v133, v96, v97
	s_waitcnt lgkmcnt(2)
	v_mfma_scale_f32_32x32x64_f8f6f4 v[66:81], v[122:129], v[154:161], v[66:81], v220, v220 op_sel_hi:[0,0,0]
	v_max3_f32 v133, v133, v98, v99
	v_max3_f32 v133, v133, v100, v101
	v_max3_f32 v133, v133, v102, v103
	v_max3_f32 v133, v133, v104, v105
	v_max3_f32 v133, v133, v106, v107
	v_max3_f32 v133, v133, v108, v109
	v_max3_f32 v133, v133, v110, v111
	v_max3_f32 v133, v133, v112, v113
	v_mov_b32_e32 v134, v133
	v_mov_b32_e32 v138, 1.0
	s_nop 0
	v_permlane32_swap_b32_e32 v133, v134
	v_max_f32_e32 v133, v133, v134
	v_cmp_ge_f32_e32 vcc, s88, v133
	s_cmp_eq_u64 vcc, exec
	s_cbranch_scc1 .LBB0_1739
	v_add_f32_e32 v133, -4.0, v133
	v_max_f32_e32 v133, 0, v133
	v_exp_f32_e64 v138, -v133
	v_sub_f32_e32 v97, v97, v133
	v_sub_f32_e32 v96, v96, v133
	v_sub_f32_e32 v95, v95, v133
	v_sub_f32_e32 v94, v94, v133
	v_sub_f32_e32 v93, v93, v133
	v_sub_f32_e32 v92, v92, v133
	v_sub_f32_e32 v91, v91, v133
	v_sub_f32_e32 v90, v90, v133
	v_sub_f32_e32 v89, v89, v133
	v_sub_f32_e32 v88, v88, v133
	v_sub_f32_e32 v87, v87, v133
	v_sub_f32_e32 v86, v86, v133
	v_sub_f32_e32 v85, v85, v133
	v_sub_f32_e32 v84, v84, v133
	v_sub_f32_e32 v83, v83, v133
	v_sub_f32_e32 v82, v82, v133
	v_sub_f32_e32 v113, v113, v133
	v_sub_f32_e32 v112, v112, v133
	v_sub_f32_e32 v111, v111, v133
	v_sub_f32_e32 v110, v110, v133
	v_sub_f32_e32 v109, v109, v133
	v_sub_f32_e32 v108, v108, v133
	v_sub_f32_e32 v107, v107, v133
	v_sub_f32_e32 v106, v106, v133
	v_sub_f32_e32 v105, v105, v133
	v_sub_f32_e32 v104, v104, v133
	v_sub_f32_e32 v103, v103, v133
	v_sub_f32_e32 v102, v102, v133
	v_sub_f32_e32 v101, v101, v133
	v_sub_f32_e32 v100, v100, v133
	v_sub_f32_e32 v99, v99, v133
	v_sub_f32_e32 v98, v98, v133
	v_sub_f32_e32 v65, v65, v133
	v_sub_f32_e32 v64, v64, v133
	v_sub_f32_e32 v63, v63, v133
	v_sub_f32_e32 v62, v62, v133
	v_sub_f32_e32 v61, v61, v133
	v_sub_f32_e32 v60, v60, v133
	v_sub_f32_e32 v59, v59, v133
	v_sub_f32_e32 v58, v58, v133
	v_sub_f32_e32 v57, v57, v133
	v_sub_f32_e32 v56, v56, v133
	v_sub_f32_e32 v55, v55, v133
	v_sub_f32_e32 v54, v54, v133
	v_sub_f32_e32 v53, v53, v133
	v_sub_f32_e32 v52, v52, v133
	v_sub_f32_e32 v51, v51, v133
	v_sub_f32_e32 v50, v50, v133
